# stack: E1+E3+E25 plus batched split-K reduce loads, batched down-GEMM residual loads, up-GEMM epilogue VALU cut
# speedup vs baseline: 1.0031x; 1.0015x over previous
.LBB0_1080:
	s_andn2_b64 vcc, exec, s[38:39]
	s_cbranch_vccnz .LBB0_1083
	s_ashr_i32 s41, s40, 31
	v_mov_b32_e32 v8, 0
	s_waitcnt lgkmcnt(0)
	v_lshl_add_u64 v[2:3], s[40:41], 4, v[6:7]
	s_mov_b32 s0, 0
	s_mov_b32 s1, s4
	v_mov_b32_e32 v9, v8
	v_mov_b32_e32 v10, v8
	v_mov_b32_e32 v11, v8
	v_mov_b32_e32 v12, v8
	v_mov_b32_e32 v13, v8
	v_mov_b32_e32 v14, v8
	v_mov_b32_e32 v15, v8
	s_cmp_lg_u32 s4, 8
	s_cbranch_scc1 .LBB0_1082
	s_waitcnt lgkmcnt(0)
	v_lshl_add_u64 v[192:193], v[2:3], 0, s[60:61]
	v_lshl_add_u64 v[194:195], v[192:193], 0, s[60:61]
	v_lshl_add_u64 v[196:197], v[194:195], 0, s[60:61]
	v_lshl_add_u64 v[198:199], v[196:197], 0, s[60:61]
	v_lshl_add_u64 v[210:211], v[198:199], 0, s[60:61]
	v_lshl_add_u64 v[212:213], v[210:211], 0, s[60:61]
	v_lshl_add_u64 v[214:215], v[212:213], 0, s[60:61]
	global_load_dwordx4 v[160:163], v[2:3], off
	global_load_dwordx4 v[164:167], v[192:193], off
	global_load_dwordx4 v[168:171], v[194:195], off
	global_load_dwordx4 v[172:175], v[196:197], off
	global_load_dwordx4 v[176:179], v[198:199], off
	global_load_dwordx4 v[180:183], v[210:211], off
	global_load_dwordx4 v[184:187], v[212:213], off
	global_load_dwordx4 v[188:191], v[214:215], off
	s_waitcnt vmcnt(7)
	v_pk_add_f32 v[8:9], v[8:9], v[160:161]
	v_pk_add_f32 v[10:11], v[10:11], v[162:163]
	s_waitcnt vmcnt(6)
	v_pk_add_f32 v[8:9], v[8:9], v[164:165]
	v_pk_add_f32 v[10:11], v[10:11], v[166:167]
	s_waitcnt vmcnt(5)
	v_pk_add_f32 v[8:9], v[8:9], v[168:169]
	v_pk_add_f32 v[10:11], v[10:11], v[170:171]
	s_waitcnt vmcnt(4)
	v_pk_add_f32 v[8:9], v[8:9], v[172:173]
	v_pk_add_f32 v[10:11], v[10:11], v[174:175]
	s_waitcnt vmcnt(3)
	v_pk_add_f32 v[12:13], v[12:13], v[176:177]
	v_pk_add_f32 v[14:15], v[14:15], v[178:179]
	s_waitcnt vmcnt(2)
	v_pk_add_f32 v[12:13], v[12:13], v[180:181]
	v_pk_add_f32 v[14:15], v[14:15], v[182:183]
	s_waitcnt vmcnt(1)
	v_pk_add_f32 v[12:13], v[12:13], v[184:185]
	v_pk_add_f32 v[14:15], v[14:15], v[186:187]
	s_waitcnt vmcnt(0)
	v_pk_add_f32 v[12:13], v[12:13], v[188:189]
	v_pk_add_f32 v[14:15], v[14:15], v[190:191]
	s_branch .LBB0_1084

.LBB0_1620:
	s_andn2_b64 vcc, exec, s[36:37]
	s_cbranch_vccnz .LBB0_1624
	s_ashr_i32 s3, s2, 31
	v_mov_b32_e32 v2, 0
	v_lshl_add_u64 v[10:11], s[2:3], 4, v[6:7]
	s_mov_b32 s3, 0
	s_mov_b32 s13, s9
	v_mov_b32_e32 v3, v2
	v_mov_b32_e32 v4, v2
	v_mov_b32_e32 v5, v2
	v_mov_b32_e32 v8, v2
	v_mov_b32_e32 v9, v2
	v_mov_b32_e32 v12, v2
	v_mov_b32_e32 v13, v2
	s_cmp_lg_u32 s9, 8
	s_cbranch_scc1 .LBB0_1622
	s_waitcnt lgkmcnt(0)
	v_lshl_add_u64 v[192:193], v[10:11], 0, s[54:55]
	v_lshl_add_u64 v[194:195], v[192:193], 0, s[54:55]
	v_lshl_add_u64 v[196:197], v[194:195], 0, s[54:55]
	v_lshl_add_u64 v[198:199], v[196:197], 0, s[54:55]
	v_lshl_add_u64 v[210:211], v[198:199], 0, s[54:55]
	v_lshl_add_u64 v[212:213], v[210:211], 0, s[54:55]
	v_lshl_add_u64 v[214:215], v[212:213], 0, s[54:55]
	global_load_dwordx4 v[160:163], v[10:11], off
	global_load_dwordx4 v[164:167], v[192:193], off
	global_load_dwordx4 v[168:171], v[194:195], off
	global_load_dwordx4 v[172:175], v[196:197], off
	global_load_dwordx4 v[176:179], v[198:199], off
	global_load_dwordx4 v[180:183], v[210:211], off
	global_load_dwordx4 v[184:187], v[212:213], off
	global_load_dwordx4 v[188:191], v[214:215], off
	s_waitcnt vmcnt(7)
	v_pk_add_f32 v[2:3], v[2:3], v[160:161]
	v_pk_add_f32 v[4:5], v[4:5], v[162:163]
	s_waitcnt vmcnt(6)
	v_pk_add_f32 v[2:3], v[2:3], v[164:165]
	v_pk_add_f32 v[4:5], v[4:5], v[166:167]
	s_waitcnt vmcnt(5)
	v_pk_add_f32 v[2:3], v[2:3], v[168:169]
	v_pk_add_f32 v[4:5], v[4:5], v[170:171]
	s_waitcnt vmcnt(4)
	v_pk_add_f32 v[2:3], v[2:3], v[172:173]
	v_pk_add_f32 v[4:5], v[4:5], v[174:175]
	s_waitcnt vmcnt(3)
	v_pk_add_f32 v[8:9], v[8:9], v[176:177]
	v_pk_add_f32 v[12:13], v[12:13], v[178:179]
	s_waitcnt vmcnt(2)
	v_pk_add_f32 v[8:9], v[8:9], v[180:181]
	v_pk_add_f32 v[12:13], v[12:13], v[182:183]
	s_waitcnt vmcnt(1)
	v_pk_add_f32 v[8:9], v[8:9], v[184:185]
	v_pk_add_f32 v[12:13], v[12:13], v[186:187]
	s_waitcnt vmcnt(0)
	v_pk_add_f32 v[8:9], v[8:9], v[188:189]
	v_pk_add_f32 v[12:13], v[12:13], v[190:191]
	s_branch .Lred5_join

.Lred5_join:
	v_pk_add_f32 v[4:5], v[12:13], v[4:5]
	v_pk_add_f32 v[2:3], v[8:9], v[2:3]
	s_branch .LBB0_1625
